# attention body preamble: LDS-buffer barrier moved down to the first LDS write; staging / q loads issued before it (asm guide 7.2)
# baseline (speedup 1.0000x reference)
; #define LAS __attribute__((address_space(3)))
; __device__ __forceinline__ void phase4_attn(const Args& a, LAS unsigned char* lds) {
;     ...
;                 const int bh = b * 2 + hkv, head = hkv * 4 + g;
;                 int tid = tid0; asm volatile("" : "+v"(tid));
;                 const int lane = tid & 63, r = lane & 31, h = lane >> 5, ql = 32 * half + r, pos = 64 * t + ql, tok = b * 2048 + pos;
;                 comb[hkv][0] = zero16(); comb[hkv][1] = zero16();
;                 const float g0 = gates[(size_t)tok * 24 + head * 3 + 0], g1 = gates[(size_t)tok * 24 + head * 3 + 1], g2 = gates[(size_t)tok * 24 + head * 3 + 2];
;                 __syncthreads();
;                 {
;                     const bf16_t* kc = kcmp + (size_t)bh * 128 * 64; const bf16_t* vc = vcmpT + (size_t)bh * 64 * 128;
; #pragma unroll
;                     for (int i = 0; i < 2; ++i) { const int c = tid + 512 * i;
;                         const u32x4 kv = *(const u32x4*)(kc + (size_t)c * 8);
;                         *(LAS u32x4*)(lds + A_CMPK + (c >> 3) * A_KSTR + (c & 7) * 16) = kv;
;                         const u32x4 vv = *(const u32x4*)(vc + (size_t)c * 8);
;                         LAS unsigned char* vp = lds + A_CMPV + (c >> 4) * A_CVSTR + (c & 15) * 16;
;                         *(LAS u32x2*)vp = (u32x2){vv.x, vv.y}; *(LAS u32x2*)(vp + 8) = (u32x2){vv.z, vv.w}; }
;                 }
;                 bf16x8_t qf[4];
; #pragma unroll
;                 for (int ks = 0; ks < 4; ++ks) qf[ks] = __builtin_nontemporal_load((const bf16x8_t*)(qn + (size_t)tok * 512 + head * 64 + 16 * ks + 8 * h));
;                 __syncthreads();
.LBB0_715:
	s_and_b64 s[0:1], s[64:65], exec
	v_readlane_b32 s0, v254, 29
	v_readlane_b32 s1, v254, 30
	v_mov_b32_e32 v152, v184
	s_cselect_b32 s38, s0, s1
	s_lshl_b32 s24, s38, 6
	s_waitcnt vmcnt(0)
	v_and_b32_e32 v100, 31, v152
	v_or_b32_e32 v98, s79, v100
	v_or_b32_e32 v154, s24, v98
	v_or_b32_e32 v4, s39, v154
	v_mad_i64_i32 v[0:1], s[4:5], v4, s83, v[116:117]
	global_load_dwordx3 v[112:114], v[0:1], off
	v_lshlrev_b32_e32 v0, 4, v152
	v_ashrrev_i32_e32 v153, 31, v152
	v_readlane_b32 s6, v254, 39
	v_and_b32_e32 v1, 0x70, v0
	v_and_b32_e32 v0, 0xf0, v0
	v_lshlrev_b64 v[10:11], 4, v[152:153]
	v_readlane_b32 s7, v254, 40
	v_add_u32_e32 v6, s85, v1
	v_add_u32_e32 v8, s86, v0
	v_lshl_add_u64 v[0:1], s[6:7], 0, v[10:11]
	v_readlane_b32 s8, v254, 31
	v_readlane_b32 s9, v254, 32
	global_load_dwordx4 v[16:19], v[0:1], off
	v_add_u32_e32 v14, 0x200, v152
	v_ashrrev_i32_e32 v15, 31, v14
	v_lshlrev_b64 v[12:13], 4, v[14:15]
	v_lshl_add_u64 v[36:37], s[8:9], 0, v[10:11]
	global_load_dwordx4 v[20:23], v[36:37], off
	v_lshl_add_u64 v[36:37], s[6:7], 0, v[12:13]
	global_load_dwordx4 v[24:27], v[36:37], off
	v_lshl_add_u64 v[36:37], s[8:9], 0, v[12:13]
	global_load_dwordx4 v[28:31], v[36:37], off
	v_readlane_b32 s4, v254, 24
	v_readlane_b32 s5, v254, 25
	v_ashrrev_i32_e32 v5, 31, v4
	v_bfe_u32 v101, v152, 5, 1
	v_lshlrev_b64 v[72:73], 10, v[4:5]
	v_lshlrev_b32_e32 v118, 4, v101
	v_lshl_add_u64 v[0:1], s[4:5], 0, v[72:73]
	v_lshl_add_u64 v[4:5], v[0:1], 0, v[118:119]
	global_load_dwordx4 v[0:3], v[4:5], off nt
	global_load_dwordx4 v[74:77], v[4:5], off offset:32 nt
	global_load_dwordx4 v[68:71], v[4:5], off offset:64 nt
	global_load_dwordx4 v[64:67], v[4:5], off offset:96 nt
	v_ashrrev_i32_e32 v99, 3, v152
	v_ashrrev_i32_e32 v7, 4, v152
	v_mul_u32_u24_e32 v153, 0x90, v100
	v_add3_u32 v82, s85, v118, v153
	v_mad_u32_u24 v32, v99, s87, v6
	v_mad_u32_u24 v33, v7, s94, v8
	v_add_u32_e32 v35, 0x2100, v33
	s_cmp_gt_u32 s38, 15
	s_cselect_b64 s[0:1], -1, 0
	s_cmp_lt_u32 s38, 16
	s_mov_b64 s[2:3], -1
	s_cselect_b64 s[62:63], -1, 0
	s_waitcnt lgkmcnt(0)
	s_barrier
	s_waitcnt vmcnt(7)
	ds_write_b128 v32, v[16:19]
	s_waitcnt vmcnt(6)
	ds_write2_b64 v33, v[20:21], v[22:23] offset1:1
	s_waitcnt vmcnt(5)
	ds_write_b128 v32, v[24:27] offset:9216
	s_waitcnt vmcnt(4)
	ds_write2_b64 v35, v[28:29], v[30:31] offset1:1
	s_waitcnt lgkmcnt(0)
	s_barrier
	s_waitcnt vmcnt(0)
	v_mov_b32_e32 v84, v0
	v_mov_b32_e32 v85, v1
	v_mov_b32_e32 v86, v2
	v_mov_b32_e32 v87, v3
	v_lshlrev_b32_e32 v155, 2, v101
	v_lshlrev_b32_e32 v156, 3, v101
	v_mul_u32_u24_e32 v157, 0x108, v100
	v_add3_u32 v244, s86, v156, v157
	v_add_u32_e32 v245, 0x2000, v244
	v_lshlrev_b32_e32 v239, 4, v155
	v_sub_u32_e32 v236, v154, v239
	v_subrev_u32_e32 v236, 31, v236
	v_ashrrev_i32_e32 v236, 4, v236
	v_cmp_lt_i32_e32 vcc, v185, v188
	s_nop 1
	v_cndmask_b32_e32 v239, v115, v185, vcc
	v_lshlrev_b32_e32 v193, 2, v239
	v_mov_b32_e32 v0, 0
	v_mov_b32_e32 v1, 0
	v_mov_b32_e32 v2, 0
	v_mov_b32_e32 v3, 0
	v_mov_b32_e32 v4, 0
	v_mov_b32_e32 v5, 0
	v_mov_b32_e32 v6, 0
	v_mov_b32_e32 v7, 0
	v_mov_b32_e32 v8, 0
	v_mov_b32_e32 v9, 0
	v_mov_b32_e32 v10, 0
	v_mov_b32_e32 v11, 0
	v_mov_b32_e32 v12, 0
	v_mov_b32_e32 v13, 0
	v_mov_b32_e32 v14, 0
	v_mov_b32_e32 v15, 0
	v_mov_b32_e32 v16, 0
	v_mov_b32_e32 v17, 0
	v_mov_b32_e32 v18, 0
	v_mov_b32_e32 v19, 0
	v_mov_b32_e32 v20, 0
	v_mov_b32_e32 v21, 0
	v_mov_b32_e32 v22, 0
	v_mov_b32_e32 v23, 0
	v_mov_b32_e32 v24, 0
	v_mov_b32_e32 v25, 0
	v_mov_b32_e32 v26, 0
	v_mov_b32_e32 v27, 0
	v_mov_b32_e32 v28, 0
	v_mov_b32_e32 v29, 0
	v_mov_b32_e32 v30, 0
	v_mov_b32_e32 v31, 0
	v_mov_b32_e32 v160, 0
	v_mov_b32_e32 v161, 0
	v_mov_b32_e32 v162, 0
	v_mov_b32_e32 v163, 0
	v_mov_b32_e32 v164, 0
	v_mov_b32_e32 v165, 0
	v_mov_b32_e32 v166, 0
	v_mov_b32_e32 v167, 0
	v_mov_b32_e32 v168, 0
	v_mov_b32_e32 v169, 0
	v_mov_b32_e32 v170, 0
	v_mov_b32_e32 v171, 0
	v_mov_b32_e32 v172, 0
	v_mov_b32_e32 v173, 0
	v_mov_b32_e32 v174, 0
	v_mov_b32_e32 v175, 0
	v_mov_b32_e32 v176, 0
	v_mov_b32_e32 v177, 0
	v_mov_b32_e32 v178, 0
	v_mov_b32_e32 v179, 0
	v_mov_b32_e32 v180, 0
	v_mov_b32_e32 v181, 0
	v_mov_b32_e32 v182, 0
	v_mov_b32_e32 v183, 0
	v_mov_b32_e32 v246, 0
	v_mov_b32_e32 v247, 0
	v_mov_b32_e32 v248, 0
	v_mov_b32_e32 v249, 0
	v_mov_b32_e32 v250, 0
	v_mov_b32_e32 v251, 0
	v_mov_b32_e32 v252, 0
	v_mov_b32_e32 v253, 0
	v_readfirstlane_b32 s7, v152
	s_bfe_u32 s7, s7, 0x10006
	s_lshl_b32 s9, s38, 1
	s_add_i32 s7, s7, s9
	s_lshr_b32 s7, s7, 4
	s_cmp_eq_u32 s7, 0
	s_cbranch_scc1 .Lc0_n1
	s_cmp_eq_u32 s7, 1
	s_cbranch_scc1 .Lc0_n2
	s_cmp_eq_u32 s7, 2
	s_cbranch_scc1 .Lc0_n3
	s_branch .Lc0_n4

; #define LAS __attribute__((address_space(3)))
; __device__ __forceinline__ void phase4_attn(const Args& a, LAS unsigned char* lds) {
;     ...
;                 const int bh = b * 2 + hkv, head = hkv * 4 + g;
;                 int tid = tid0; asm volatile("" : "+v"(tid));
;                 const int lane = tid & 63, r = lane & 31, h = lane >> 5, ql = 32 * half + r, pos = 64 * t + ql, tok = b * 2048 + pos;
;                 comb[hkv][0] = zero16(); comb[hkv][1] = zero16();
;                 const float g0 = gates[(size_t)tok * 24 + head * 3 + 0], g1 = gates[(size_t)tok * 24 + head * 3 + 1], g2 = gates[(size_t)tok * 24 + head * 3 + 2];
;                 __syncthreads();
;                 {
;                     const bf16_t* kc = kcmp + (size_t)bh * 128 * 64; const bf16_t* vc = vcmpT + (size_t)bh * 64 * 128;
; #pragma unroll
;                     for (int i = 0; i < 2; ++i) { const int c = tid + 512 * i;
;                         const u32x4 kv = *(const u32x4*)(kc + (size_t)c * 8);
;                         *(LAS u32x4*)(lds + A_CMPK + (c >> 3) * A_KSTR + (c & 7) * 16) = kv;
;                         const u32x4 vv = *(const u32x4*)(vc + (size_t)c * 8);
;                         LAS unsigned char* vp = lds + A_CMPV + (c >> 4) * A_CVSTR + (c & 15) * 16;
;                         *(LAS u32x2*)vp = (u32x2){vv.x, vv.y}; *(LAS u32x2*)(vp + 8) = (u32x2){vv.z, vv.w}; }
;                 }
;                 bf16x8_t qf[4];
; #pragma unroll
;                 for (int ks = 0; ks < 4; ++ks) qf[ks] = __builtin_nontemporal_load((const bf16x8_t*)(qn + (size_t)tok * 512 + head * 64 + 16 * ks + 8 * h));
;                 __syncthreads();
.LBB0_794:
	v_mov_b32_e32 v152, v184
	v_readlane_b32 s0, v254, 57
	s_waitcnt vmcnt(2)
	v_and_b32_e32 v100, 31, v152
	v_or_b32_e32 v98, s79, v100
	v_or_b32_e32 v194, s24, v98
	v_readlane_b32 s1, v254, 58
	v_or_b32_e32 v4, s39, v194
	v_ashrrev_i32_e32 v153, 31, v152
	v_mov_b64_e32 v[0:1], s[0:1]
	v_mad_i64_i32 v[0:1], s[0:1], v4, s83, v[0:1]
	global_load_dwordx3 v[112:114], v[0:1], off
	v_lshlrev_b32_e32 v0, 4, v152
	v_readlane_b32 s4, v254, 35
	v_and_b32_e32 v1, 0x70, v0
	v_and_b32_e32 v0, 0xf0, v0
	v_lshlrev_b64 v[10:11], 4, v[152:153]
	v_readlane_b32 s5, v254, 36
	v_add_u32_e32 v6, s85, v1
	v_add_u32_e32 v8, s86, v0
	v_lshl_add_u64 v[0:1], s[4:5], 0, v[10:11]
	s_nop 0
	global_load_dwordx4 v[16:19], v[0:1], off
	v_add_u32_e32 v14, 0x200, v152
	v_ashrrev_i32_e32 v15, 31, v14
	v_lshlrev_b64 v[12:13], 4, v[14:15]
	v_lshl_add_u64 v[36:37], s[52:53], 0, v[10:11]
	global_load_dwordx4 v[20:23], v[36:37], off
	v_lshl_add_u64 v[36:37], s[4:5], 0, v[12:13]
	global_load_dwordx4 v[24:27], v[36:37], off
	v_lshl_add_u64 v[36:37], s[52:53], 0, v[12:13]
	global_load_dwordx4 v[28:31], v[36:37], off
	v_readlane_b32 s0, v254, 59
	v_readlane_b32 s1, v254, 60
	v_ashrrev_i32_e32 v5, 31, v4
	v_bfe_u32 v101, v152, 5, 1
	v_lshlrev_b64 v[72:73], 10, v[4:5]
	v_lshlrev_b32_e32 v118, 4, v101
	v_lshl_add_u64 v[0:1], s[0:1], 0, v[72:73]
	v_lshl_add_u64 v[4:5], v[0:1], 0, v[118:119]
	global_load_dwordx4 v[0:3], v[4:5], off nt
	global_load_dwordx4 v[74:77], v[4:5], off offset:32 nt
	global_load_dwordx4 v[68:71], v[4:5], off offset:64 nt
	global_load_dwordx4 v[64:67], v[4:5], off offset:96 nt
	v_ashrrev_i32_e32 v99, 3, v152
	v_ashrrev_i32_e32 v7, 4, v152
	v_mul_u32_u24_e32 v153, 0x90, v100
	v_add3_u32 v82, s85, v118, v153
	v_mad_u32_u24 v32, v99, s87, v6
	v_mad_u32_u24 v33, v7, s94, v8
	v_add_u32_e32 v35, 0x2100, v33
	s_barrier
	s_waitcnt vmcnt(7)
	ds_write_b128 v32, v[16:19]
	s_waitcnt vmcnt(6)
	ds_write2_b64 v33, v[20:21], v[22:23] offset1:1
	s_waitcnt vmcnt(5)
	ds_write_b128 v32, v[24:27] offset:9216
	s_waitcnt vmcnt(4)
	ds_write2_b64 v35, v[28:29], v[30:31] offset1:1
	s_waitcnt lgkmcnt(0)
	s_barrier
	s_waitcnt vmcnt(0)
	v_mov_b32_e32 v84, v0
	v_mov_b32_e32 v85, v1
	v_mov_b32_e32 v86, v2
	v_mov_b32_e32 v87, v3
	v_lshlrev_b32_e32 v195, 2, v101
	v_lshlrev_b32_e32 v196, 3, v101
	v_mul_u32_u24_e32 v197, 0x108, v100
	v_add3_u32 v244, s86, v196, v197
	v_add_u32_e32 v245, 0x2000, v244
	v_lshlrev_b32_e32 v239, 4, v195
	v_sub_u32_e32 v236, v194, v239
	v_subrev_u32_e32 v236, 31, v236
	v_ashrrev_i32_e32 v236, 4, v236
	v_mov_b32_e32 v0, 0
	v_mov_b32_e32 v1, 0
	v_mov_b32_e32 v2, 0
	v_mov_b32_e32 v3, 0
	v_mov_b32_e32 v4, 0
	v_mov_b32_e32 v5, 0
	v_mov_b32_e32 v6, 0
	v_mov_b32_e32 v7, 0
	v_mov_b32_e32 v8, 0
	v_mov_b32_e32 v9, 0
	v_mov_b32_e32 v10, 0
	v_mov_b32_e32 v11, 0
	v_mov_b32_e32 v12, 0
	v_mov_b32_e32 v13, 0
	v_mov_b32_e32 v14, 0
	v_mov_b32_e32 v15, 0
	v_mov_b32_e32 v16, 0
	v_mov_b32_e32 v17, 0
	v_mov_b32_e32 v18, 0
	v_mov_b32_e32 v19, 0
	v_mov_b32_e32 v20, 0
	v_mov_b32_e32 v21, 0
	v_mov_b32_e32 v22, 0
	v_mov_b32_e32 v23, 0
	v_mov_b32_e32 v24, 0
	v_mov_b32_e32 v25, 0
	v_mov_b32_e32 v26, 0
	v_mov_b32_e32 v27, 0
	v_mov_b32_e32 v28, 0
	v_mov_b32_e32 v29, 0
	v_mov_b32_e32 v30, 0
	v_mov_b32_e32 v31, 0
	v_mov_b32_e32 v160, 0
	v_mov_b32_e32 v161, 0
	v_mov_b32_e32 v162, 0
	v_mov_b32_e32 v163, 0
	v_mov_b32_e32 v164, 0
	v_mov_b32_e32 v165, 0
	v_mov_b32_e32 v166, 0
	v_mov_b32_e32 v167, 0
	v_mov_b32_e32 v168, 0
	v_mov_b32_e32 v169, 0
	v_mov_b32_e32 v170, 0
	v_mov_b32_e32 v171, 0
	v_mov_b32_e32 v172, 0
	v_mov_b32_e32 v173, 0
	v_mov_b32_e32 v174, 0
	v_mov_b32_e32 v175, 0
	v_mov_b32_e32 v176, 0
	v_mov_b32_e32 v177, 0
	v_mov_b32_e32 v178, 0
	v_mov_b32_e32 v179, 0
	v_mov_b32_e32 v180, 0
	v_mov_b32_e32 v181, 0
	v_mov_b32_e32 v182, 0
	v_mov_b32_e32 v183, 0
	v_mov_b32_e32 v246, 0
	v_mov_b32_e32 v247, 0
	v_mov_b32_e32 v248, 0
	v_mov_b32_e32 v249, 0
	v_mov_b32_e32 v250, 0
	v_mov_b32_e32 v251, 0
	v_mov_b32_e32 v252, 0
	v_mov_b32_e32 v253, 0
	v_readfirstlane_b32 s7, v152
	s_bfe_u32 s7, s7, 0x10006
	s_lshl_b32 s9, s38, 1
	s_add_i32 s7, s7, s9
	s_lshr_b32 s7, s7, 4
	s_cmp_eq_u32 s7, 0
	s_cbranch_scc1 .Lc1_n1
	s_cmp_eq_u32 s7, 1
	s_cbranch_scc1 .Lc1_n2
	s_cmp_eq_u32 s7, 2
	s_cbranch_scc1 .Lc1_n3
	s_branch .Lc1_n4
